# the 64 left-over in-proj tiles run after (not before) the pooling/kv items of workgroups 0..63
# speedup vs baseline: 1.0209x; 1.0061x over previous
; __device__ __forceinline__ void run_phase(const Params& p, int ph, LAS unsigned char* lds, const int tid, const int bid) {
;     ...
;     } else if (sub == 1) { if (PH_MASK & 4)
;         for (int it = bid; it < 1024 + 544 + 580; it += G) {
;             if (it < 1024) sample_ret_unit(p, l, it, lds, tid);
;             else if (it < 1568) kv_unit(p, it - 1024, lds, tid);
;             else pool_item(p, l, it - 1568, tid);
;         }
.LBB0_447:
	s_andn2_b64 vcc, exec, s[0:1]
	s_cbranch_vccnz .LBB0_582
	v_readlane_b32 s0, v254, 48
	s_and_b32 s0, 0xffff, s0
	s_cmp_gt_i32 s0, 0
	s_mov_b64 s[0:1], -1
	s_cbranch_scc0 .LBB0_547
	s_cmpk_gt_i32 s82, 0x863
	s_cbranch_scc1 .LBB0_546
	v_readlane_b32 s0, v254, 46
	v_readlane_b32 s1, v254, 47
	s_mov_b32 s1, s91
	v_readlane_b32 s8, v253, 57
	s_lshl_b64 s[22:23], s[0:1], 7
	s_lshl_b64 s[24:25], s[0:1], 2
	s_lshl_b64 s[26:27], s[0:1], 10
	s_mov_b32 s6, s0
	s_lshl_b64 s[0:1], s[0:1], 13
	v_readlane_b32 s10, v253, 59
	v_readlane_b32 s11, v253, 60
	s_add_u32 s34, s10, s0
	v_writelane_b32 v254, s6, 46
	s_addc_u32 s35, s11, s1
	s_mov_b32 s38, s82
	s_cmpk_lg_u32 s42, 0x100
	s_cbranch_scc1 .Lp2_fwd0
	s_bitcmp1_b32 s82, 3
	s_cbranch_scc1 .Lz2_ibwd
	s_mov_b32 s0, 0
	s_add_i32 s38, s82, 0xffffffc0
	s_cmpk_gt_u32 s82, 63
	s_cbranch_scc1 .Lz2_iset
	s_mov_b32 s0, 1
	s_add_i32 s38, s82, 0x3c0
	s_branch .Lz2_iset

; __device__ __forceinline__ void run_phase(const Params& p, int ph, LAS unsigned char* lds, const int tid, const int bid) {
;     ...
;         for (int it = bid; it < 1024 + 544 + 580; it += G) {
;             if (it < 1024) sample_ret_unit(p, l, it, lds, tid);
;             else if (it < 1568) kv_unit(p, it - 1024, lds, tid);
;             else pool_item(p, l, it - 1568, tid);
;         }
.LBB0_546:
	s_cmpk_lg_u32 s42, 0x100
	s_cbranch_scc1 .Lz3_no
	s_cmpk_gt_u32 s82, 63
	s_cbranch_scc1 .Lz3_no
	s_mov_b32 s19, 1
	s_nop 0
	v_writelane_b32 v255, s19, 6
	s_waitcnt vmcnt(0) lgkmcnt(0)
	s_barrier
	s_branch .Lz1_p1entry

; #define G_WAIT_V(n) asm volatile("s_waitcnt vmcnt(" #n ")" ::: "memory")
; #define G_BAR __builtin_amdgcn_s_barrier()
; template <class Epi, class Sched>
; __device__ __forceinline__ void gemm_phase(LAS unsigned char* lds, const Sched& S, const Epi& E, const int K, const int lda, const int ldb, const int tid) {
;     ...
;         const bool keep = E(acc, cur, wr, wc, fr, fq);
;         if (!has_next) break;
;         if (!keep)
; #pragma unroll
;         for (int a = 0; a < 2; ++a)
; #pragma unroll
;             for (int b = 0; b < 2; ++b)
; #pragma unroll
;                 for (int m = 0; m < 4; ++m)
; #pragma unroll
;                     for (int n = 0; n < 2; ++n) acc[a][b][m][n] = (f32x4){0.f, 0.f, 0.f, 0.f};
;         cur = nxt; cA = nA; cB = nB; ++ui;
;     }
;     G_WAIT_V(0);
;     if (wr == 0) G_BAR;
;     G_BAR;
.LBB0_581:
	s_barrier
	v_readlane_b32 s18, v255, 6
	s_mov_b32 s19, 0
	s_cmp_eq_u32 s18, 0
	s_cbranch_scc1 .Lz1_noforce
	v_writelane_b32 v255, s19, 6
	s_branch .LBB0_582
